# grid barrier: TOP counter polled directly by all WGs, no TOPGEN/XGEN relay
# speedup vs baseline: 1.0048x; 1.0048x over previous
_Z10fwd_kernel4Args:
	s_mov_b32 s99, 0
	s_load_dword s3, s[0:1], 0xd8
	s_load_dwordx4 s[76:79], s[0:1], 0xc0
	s_load_dwordx2 s[60:61], s[0:1], 0xd0
	v_and_b32_e32 v185, 0x3ff, v0
	s_add_u32 s6, s0, 0xd0
	v_readfirstlane_b32 s74, v185
	s_addc_u32 s7, s1, 0
	v_cmp_gt_u32_e32 vcc, 16, v185
	s_waitcnt lgkmcnt(0)
	v_writelane_b32 v242, s3, 0
	s_and_saveexec_b64 s[4:5], vcc
	v_lshl_add_u32 v1, v185, 2, 0
	v_add_u32_e32 v1, 0x21000, v1
	v_mov_b32_e32 v2, 0
	ds_write_b32 v1, v2
	s_or_b64 exec, exec, s[4:5]
	s_waitcnt lgkmcnt(0)
	s_barrier
	s_getreg_b32 s3, hwreg(HW_REG_XCC_ID, 0, 4)
	s_and_b32 s84, s3, 15
	v_cmp_eq_u32_e64 s[8:9], 0, v185
	s_mov_b64 s[4:5], exec
	s_nop 0
	v_writelane_b32 v242, s8, 1
	s_nop 1
	v_writelane_b32 v242, s9, 2
	s_and_b64 s[8:9], s[4:5], s[8:9]
	s_mov_b64 exec, s[8:9]
	s_cbranch_execz .LBB0_5
	s_mov_b64 s[8:9], exec
	v_mbcnt_lo_u32_b32 v1, s8, 0
	v_mbcnt_hi_u32_b32 v1, s9, v1
	v_cmp_eq_u32_e32 vcc, 0, v1
	s_and_b64 s[10:11], exec, vcc
	s_mov_b64 exec, s[10:11]
	s_cbranch_execz .LBB0_5
	s_lshl_b32 s3, s84, 8
	s_bcnt1_i32_b64 s8, s[8:9]
	v_mov_b32_e32 v1, s3
	v_mov_b32_e32 v2, s8
	global_atomic_add v1, v2, s[76:77] offset:1024

.LBB0_100:
	s_or_b64 exec, exec, s[0:1]
	s_waitcnt lgkmcnt(0)
	s_barrier
	s_add_u32 s99, s99, 1

.LBB0_367:
	s_cmp_gt_i32 s79, 2
	s_cselect_b64 s[4:5], -1, 0
	s_and_b64 s[0:1], s[0:1], s[4:5]
	s_andn2_b64 vcc, exec, s[0:1]
	s_cbranch_vccnz .LBB0_421
	s_waitcnt vmcnt(0) lgkmcnt(0)
	s_barrier
	v_readlane_b32 s12, v242, 1
	v_readlane_b32 s13, v242, 2
	s_mov_b64 s[14:15], exec
	s_and_b64 s[12:13], s[14:15], s[12:13]
	s_mov_b64 exec, s[12:13]
	s_cbranch_execz .Lxb_done_1
	v_mov_b32_e32 v0, 0x21020
	ds_read2_b32 v[2:3], v0 offset1:1
	s_lshl_b32 s16, s84, 8
	s_add_u32 s16, s76, s16
	s_addc_u32 s17, s77, 0
	v_mov_b32_e32 v1, 0x1000
	v_mov_b32_e32 v4, 1
	global_atomic_add v5, v1, v4, s[16:17] offset:1024 sc0
	s_add_u32 s21, s99, 1
	s_waitcnt vmcnt(0) lgkmcnt(0)
	v_readfirstlane_b32 s18, v5
	v_readfirstlane_b32 s19, v2
	v_readfirstlane_b32 s20, v3
	v_mov_b32_e32 v1, 0x3000
	s_mul_i32 s22, s19, s21
	s_mul_i32 s23, s20, s21
	s_add_u32 s18, s18, 1
	s_cmp_lg_u32 s18, s22
	s_cbranch_scc1 .Lxb_spin_1
	buffer_wbl2 sc1
	s_waitcnt vmcnt(0)
	global_atomic_add v1, v4, s[76:77] offset:1024
.Lxb_spin_1:
	global_load_dword v6, v1, s[76:77] offset:1024 sc1
	s_waitcnt vmcnt(0)
	v_readfirstlane_b32 s24, v6
	s_sub_u32 s24, s24, s23
	s_cmp_ge_i32 s24, 0
	s_cbranch_scc1 .Lxb_acq_1
	s_sleep 1
	s_branch .Lxb_spin_1
.Lxb_acq_1:
	buffer_inv sc1
	s_waitcnt vmcnt(0)
.Lxb_done_1:
	s_mov_b64 exec, s[14:15]
	s_add_u32 s99, s99, 1
	s_barrier

.LBB0_470:
	s_cmp_gt_i32 s79, 3
	s_cselect_b64 s[0:1], -1, 0
	s_and_b64 s[4:5], s[10:11], s[0:1]
	v_readlane_b32 s64, v242, 58
	s_andn2_b64 vcc, exec, s[4:5]
	v_readlane_b32 s65, v242, 59
	s_cbranch_vccnz .LBB0_524
	s_waitcnt vmcnt(0) lgkmcnt(0)
	s_barrier
	v_readlane_b32 s12, v242, 1
	v_readlane_b32 s13, v242, 2
	s_mov_b64 s[14:15], exec
	s_and_b64 s[12:13], s[14:15], s[12:13]
	s_mov_b64 exec, s[12:13]
	s_cbranch_execz .Lxb_done_2
	v_mov_b32_e32 v0, 0x21020
	ds_read2_b32 v[2:3], v0 offset1:1
	s_lshl_b32 s16, s84, 8
	s_add_u32 s16, s76, s16
	s_addc_u32 s17, s77, 0
	v_mov_b32_e32 v1, 0x1000
	v_mov_b32_e32 v4, 1
	global_atomic_add v5, v1, v4, s[16:17] offset:1024 sc0
	s_add_u32 s21, s99, 1
	s_waitcnt vmcnt(0) lgkmcnt(0)
	v_readfirstlane_b32 s18, v5
	v_readfirstlane_b32 s19, v2
	v_readfirstlane_b32 s20, v3
	v_mov_b32_e32 v1, 0x3000
	s_mul_i32 s22, s19, s21
	s_mul_i32 s23, s20, s21
	s_add_u32 s18, s18, 1
	s_cmp_lg_u32 s18, s22
	s_cbranch_scc1 .Lxb_spin_2
	buffer_wbl2 sc1
	s_waitcnt vmcnt(0)
	global_atomic_add v1, v4, s[76:77] offset:1024

.LBB0_759:
	s_cmp_gt_i32 s79, 4
	s_cselect_b64 s[0:1], -1, 0
	s_and_b64 s[0:1], s[24:25], s[0:1]
	s_andn2_b64 vcc, exec, s[0:1]
	s_cbranch_vccnz .LBB0_813
	s_waitcnt vmcnt(0) lgkmcnt(0)
	s_barrier
	v_readlane_b32 s12, v242, 1
	v_readlane_b32 s13, v242, 2
	s_mov_b64 s[14:15], exec
	s_and_b64 s[12:13], s[14:15], s[12:13]
	s_mov_b64 exec, s[12:13]
	s_cbranch_execz .Lxb_done_3
	v_mov_b32_e32 v0, 0x21020
	ds_read2_b32 v[2:3], v0 offset1:1
	s_lshl_b32 s16, s84, 8
	s_add_u32 s16, s76, s16
	s_addc_u32 s17, s77, 0
	v_mov_b32_e32 v1, 0x1000
	v_mov_b32_e32 v4, 1
	global_atomic_add v5, v1, v4, s[16:17] offset:1024 sc0
	s_add_u32 s21, s99, 1
	s_waitcnt vmcnt(0) lgkmcnt(0)
	v_readfirstlane_b32 s18, v5
	v_readfirstlane_b32 s19, v2
	v_readfirstlane_b32 s20, v3
	v_mov_b32_e32 v1, 0x3000
	s_mul_i32 s22, s19, s21
	s_mul_i32 s23, s20, s21
	s_add_u32 s18, s18, 1
	s_cmp_lg_u32 s18, s22
	s_cbranch_scc1 .Lxb_spin_3
	buffer_wbl2 sc1
	s_waitcnt vmcnt(0)
	global_atomic_add v1, v4, s[76:77] offset:1024

.LBB0_882:
	s_cmp_gt_i32 s79, 6
	s_cselect_b64 s[0:1], -1, 0
	s_and_b64 s[0:1], s[6:7], s[0:1]
	s_andn2_b64 vcc, exec, s[0:1]
	s_cbranch_vccnz .LBB0_936
	s_waitcnt vmcnt(0) lgkmcnt(0)
	s_barrier
	v_readlane_b32 s12, v242, 1
	v_readlane_b32 s13, v242, 2
	s_mov_b64 s[14:15], exec
	s_and_b64 s[12:13], s[14:15], s[12:13]
	s_mov_b64 exec, s[12:13]
	s_cbranch_execz .Lxb_done_4
	v_mov_b32_e32 v0, 0x21020
	ds_read2_b32 v[2:3], v0 offset1:1
	s_lshl_b32 s16, s84, 8
	s_add_u32 s16, s76, s16
	s_addc_u32 s17, s77, 0
	v_mov_b32_e32 v1, 0x1000
	v_mov_b32_e32 v4, 1
	global_atomic_add v5, v1, v4, s[16:17] offset:1024 sc0
	s_add_u32 s21, s99, 1
	s_waitcnt vmcnt(0) lgkmcnt(0)
	v_readfirstlane_b32 s18, v5
	v_readfirstlane_b32 s19, v2
	v_readfirstlane_b32 s20, v3
	v_mov_b32_e32 v1, 0x3000
	s_mul_i32 s22, s19, s21
	s_mul_i32 s23, s20, s21
	s_add_u32 s18, s18, 1
	s_cmp_lg_u32 s18, s22
	s_cbranch_scc1 .Lxb_spin_4
	buffer_wbl2 sc1
	s_waitcnt vmcnt(0)
	global_atomic_add v1, v4, s[76:77] offset:1024

.LBB0_952:
	s_cmp_gt_i32 s79, 8
	s_cselect_b64 s[6:7], -1, 0
	s_and_b64 s[0:1], s[4:5], s[6:7]
	s_andn2_b64 vcc, exec, s[0:1]
	s_cbranch_vccnz .LBB0_1006
	s_waitcnt vmcnt(0) lgkmcnt(0)
	s_barrier
	v_readlane_b32 s12, v242, 1
	v_readlane_b32 s13, v242, 2
	s_mov_b64 s[14:15], exec
	s_and_b64 s[12:13], s[14:15], s[12:13]
	s_mov_b64 exec, s[12:13]
	s_cbranch_execz .Lxb_done_5
	v_mov_b32_e32 v0, 0x21020
	ds_read2_b32 v[2:3], v0 offset1:1
	s_lshl_b32 s16, s84, 8
	s_add_u32 s16, s76, s16
	s_addc_u32 s17, s77, 0
	v_mov_b32_e32 v1, 0x1000
	v_mov_b32_e32 v4, 1
	global_atomic_add v5, v1, v4, s[16:17] offset:1024 sc0
	s_add_u32 s21, s99, 1
	s_waitcnt vmcnt(0) lgkmcnt(0)
	v_readfirstlane_b32 s18, v5
	v_readfirstlane_b32 s19, v2
	v_readfirstlane_b32 s20, v3
	v_mov_b32_e32 v1, 0x3000
	s_mul_i32 s22, s19, s21
	s_mul_i32 s23, s20, s21
	s_add_u32 s18, s18, 1
	s_cmp_lg_u32 s18, s22
	s_cbranch_scc1 .Lxb_spin_5
	buffer_wbl2 sc1
	s_waitcnt vmcnt(0)
	global_atomic_add v1, v4, s[76:77] offset:1024

.LBB0_1051:
	s_cmp_gt_i32 s79, 9
	s_cselect_b64 s[4:5], -1, 0
	s_and_b64 s[0:1], s[0:1], s[4:5]
	s_andn2_b64 vcc, exec, s[0:1]
	s_cbranch_vccnz .LBB0_1105
	s_waitcnt vmcnt(0) lgkmcnt(0)
	s_barrier
	v_readlane_b32 s12, v242, 1
	v_readlane_b32 s13, v242, 2
	s_mov_b64 s[14:15], exec
	s_and_b64 s[12:13], s[14:15], s[12:13]
	s_mov_b64 exec, s[12:13]
	s_cbranch_execz .Lxb_done_6
	v_mov_b32_e32 v0, 0x21020
	ds_read2_b32 v[2:3], v0 offset1:1
	s_lshl_b32 s16, s84, 8
	s_add_u32 s16, s76, s16
	s_addc_u32 s17, s77, 0
	v_mov_b32_e32 v1, 0x1000
	v_mov_b32_e32 v4, 1
	global_atomic_add v5, v1, v4, s[16:17] offset:1024 sc0
	s_add_u32 s21, s99, 1
	s_waitcnt vmcnt(0) lgkmcnt(0)
	v_readfirstlane_b32 s18, v5
	v_readfirstlane_b32 s19, v2
	v_readfirstlane_b32 s20, v3
	v_mov_b32_e32 v1, 0x3000
	s_mul_i32 s22, s19, s21
	s_mul_i32 s23, s20, s21
	s_add_u32 s18, s18, 1
	s_cmp_lg_u32 s18, s22
	s_cbranch_scc1 .Lxb_spin_6
	buffer_wbl2 sc1
	s_waitcnt vmcnt(0)
	global_atomic_add v1, v4, s[76:77] offset:1024

.LBB0_1246:
	s_cmp_gt_i32 s79, 10
	s_cselect_b64 s[4:5], -1, 0
	s_and_b64 s[0:1], s[0:1], s[4:5]
	s_andn2_b64 vcc, exec, s[0:1]
	s_cbranch_vccnz .LBB0_1300
	s_waitcnt vmcnt(0) lgkmcnt(0)
	s_barrier
	v_readlane_b32 s12, v242, 1
	v_readlane_b32 s13, v242, 2
	s_mov_b64 s[14:15], exec
	s_and_b64 s[12:13], s[14:15], s[12:13]
	s_mov_b64 exec, s[12:13]
	s_cbranch_execz .Lxb_done_7
	v_mov_b32_e32 v0, 0x21020
	ds_read2_b32 v[2:3], v0 offset1:1
	s_lshl_b32 s16, s84, 8
	s_add_u32 s16, s76, s16
	s_addc_u32 s17, s77, 0
	v_mov_b32_e32 v1, 0x1000
	v_mov_b32_e32 v4, 1
	global_atomic_add v5, v1, v4, s[16:17] offset:1024 sc0
	s_add_u32 s21, s99, 1
	s_waitcnt vmcnt(0) lgkmcnt(0)
	v_readfirstlane_b32 s18, v5
	v_readfirstlane_b32 s19, v2
	v_readfirstlane_b32 s20, v3
	v_mov_b32_e32 v1, 0x3000
	s_mul_i32 s22, s19, s21
	s_mul_i32 s23, s20, s21
	s_add_u32 s18, s18, 1
	s_cmp_lg_u32 s18, s22
	s_cbranch_scc1 .Lxb_spin_7
	buffer_wbl2 sc1
	s_waitcnt vmcnt(0)
	global_atomic_add v1, v4, s[76:77] offset:1024

.LBB0_1349:
	s_cmp_gt_i32 s79, 11
	s_cselect_b64 s[4:5], -1, 0
	s_and_b64 s[0:1], s[10:11], s[4:5]
	s_andn2_b64 vcc, exec, s[0:1]
	s_cbranch_vccnz .LBB0_1403
	s_waitcnt vmcnt(0) lgkmcnt(0)
	s_barrier
	v_readlane_b32 s12, v242, 1
	v_readlane_b32 s13, v242, 2
	s_mov_b64 s[14:15], exec
	s_and_b64 s[12:13], s[14:15], s[12:13]
	s_mov_b64 exec, s[12:13]
	s_cbranch_execz .Lxb_done_8
	v_mov_b32_e32 v0, 0x21020
	ds_read2_b32 v[2:3], v0 offset1:1
	s_lshl_b32 s16, s84, 8
	s_add_u32 s16, s76, s16
	s_addc_u32 s17, s77, 0
	v_mov_b32_e32 v1, 0x1000
	v_mov_b32_e32 v4, 1
	global_atomic_add v5, v1, v4, s[16:17] offset:1024 sc0
	s_add_u32 s21, s99, 1
	s_waitcnt vmcnt(0) lgkmcnt(0)
	v_readfirstlane_b32 s18, v5
	v_readfirstlane_b32 s19, v2
	v_readfirstlane_b32 s20, v3
	v_mov_b32_e32 v1, 0x3000
	s_mul_i32 s22, s19, s21
	s_mul_i32 s23, s20, s21
	s_add_u32 s18, s18, 1
	s_cmp_lg_u32 s18, s22
	s_cbranch_scc1 .Lxb_spin_8
	buffer_wbl2 sc1
	s_waitcnt vmcnt(0)
	global_atomic_add v1, v4, s[76:77] offset:1024

.LBB0_1552:
	s_cmp_gt_i32 s79, 12
	s_cselect_b64 s[4:5], -1, 0
	s_and_b64 s[0:1], s[0:1], s[4:5]
	s_andn2_b64 vcc, exec, s[0:1]
	s_cbranch_vccnz .LBB0_1606
	s_waitcnt vmcnt(0) lgkmcnt(0)
	s_barrier
	v_readlane_b32 s12, v242, 1
	v_readlane_b32 s13, v242, 2
	s_mov_b64 s[14:15], exec
	s_and_b64 s[12:13], s[14:15], s[12:13]
	s_mov_b64 exec, s[12:13]
	s_cbranch_execz .Lxb_done_9
	v_mov_b32_e32 v0, 0x21020
	ds_read2_b32 v[2:3], v0 offset1:1
	s_lshl_b32 s16, s84, 8
	s_add_u32 s16, s76, s16
	s_addc_u32 s17, s77, 0
	v_mov_b32_e32 v1, 0x1000
	v_mov_b32_e32 v4, 1
	global_atomic_add v5, v1, v4, s[16:17] offset:1024 sc0
	s_add_u32 s21, s99, 1
	s_waitcnt vmcnt(0) lgkmcnt(0)
	v_readfirstlane_b32 s18, v5
	v_readfirstlane_b32 s19, v2
	v_readfirstlane_b32 s20, v3
	v_mov_b32_e32 v1, 0x3000
	s_mul_i32 s22, s19, s21
	s_mul_i32 s23, s20, s21
	s_add_u32 s18, s18, 1
	s_cmp_lg_u32 s18, s22
	s_cbranch_scc1 .Lxb_spin_9
	buffer_wbl2 sc1
	s_waitcnt vmcnt(0)
	global_atomic_add v1, v4, s[76:77] offset:1024

.LBB0_1655:
	s_cmp_gt_i32 s79, 13
	s_cselect_b64 s[4:5], -1, 0
	s_and_b64 s[0:1], s[10:11], s[4:5]
	s_andn2_b64 vcc, exec, s[0:1]
	s_cbranch_vccnz .LBB0_1709
	s_waitcnt vmcnt(0) lgkmcnt(0)
	s_barrier
	v_readlane_b32 s12, v242, 1
	v_readlane_b32 s13, v242, 2
	s_mov_b64 s[14:15], exec
	s_and_b64 s[12:13], s[14:15], s[12:13]
	s_mov_b64 exec, s[12:13]
	s_cbranch_execz .Lxb_done_10
	v_mov_b32_e32 v0, 0x21020
	ds_read2_b32 v[2:3], v0 offset1:1
	s_lshl_b32 s16, s84, 8
	s_add_u32 s16, s76, s16
	s_addc_u32 s17, s77, 0
	v_mov_b32_e32 v1, 0x1000
	v_mov_b32_e32 v4, 1
	global_atomic_add v5, v1, v4, s[16:17] offset:1024 sc0
	s_add_u32 s21, s99, 1
	s_waitcnt vmcnt(0) lgkmcnt(0)
	v_readfirstlane_b32 s18, v5
	v_readfirstlane_b32 s19, v2
	v_readfirstlane_b32 s20, v3
	v_mov_b32_e32 v1, 0x3000
	s_mul_i32 s22, s19, s21
	s_mul_i32 s23, s20, s21
	s_add_u32 s18, s18, 1
	s_cmp_lg_u32 s18, s22
	s_cbranch_scc1 .Lxb_spin_10
	buffer_wbl2 sc1
	s_waitcnt vmcnt(0)
	global_atomic_add v1, v4, s[76:77] offset:1024

.LBB0_1734:
	s_cmp_gt_i32 s79, 14
	s_cselect_b64 s[4:5], -1, 0
	s_and_b64 s[0:1], s[0:1], s[4:5]
	s_andn2_b64 vcc, exec, s[0:1]
	s_cbranch_vccnz .LBB0_1788
	s_waitcnt vmcnt(0) lgkmcnt(0)
	s_barrier
	v_readlane_b32 s12, v242, 1
	v_readlane_b32 s13, v242, 2
	s_mov_b64 s[14:15], exec
	s_and_b64 s[12:13], s[14:15], s[12:13]
	s_mov_b64 exec, s[12:13]
	s_cbranch_execz .Lxb_done_11
	v_mov_b32_e32 v0, 0x21020
	ds_read2_b32 v[2:3], v0 offset1:1
	s_lshl_b32 s16, s84, 8
	s_add_u32 s16, s76, s16
	s_addc_u32 s17, s77, 0
	v_mov_b32_e32 v1, 0x1000
	v_mov_b32_e32 v4, 1
	global_atomic_add v5, v1, v4, s[16:17] offset:1024 sc0
	s_add_u32 s21, s99, 1
	s_waitcnt vmcnt(0) lgkmcnt(0)
	v_readfirstlane_b32 s18, v5
	v_readfirstlane_b32 s19, v2
	v_readfirstlane_b32 s20, v3
	v_mov_b32_e32 v1, 0x3000
	s_mul_i32 s22, s19, s21
	s_mul_i32 s23, s20, s21
	s_add_u32 s18, s18, 1
	s_cmp_lg_u32 s18, s22
	s_cbranch_scc1 .Lxb_spin_11
	buffer_wbl2 sc1
	s_waitcnt vmcnt(0)
	global_atomic_add v1, v4, s[76:77] offset:1024

.LBB0_1812:
	s_cmp_gt_i32 s79, 15
	s_cselect_b64 s[4:5], -1, 0
	s_and_b64 s[0:1], s[0:1], s[4:5]
	s_andn2_b64 vcc, exec, s[0:1]
	s_cbranch_vccnz .LBB0_1866
	s_waitcnt vmcnt(0) lgkmcnt(0)
	s_barrier
	v_readlane_b32 s12, v242, 1
	v_readlane_b32 s13, v242, 2
	s_mov_b64 s[14:15], exec
	s_and_b64 s[12:13], s[14:15], s[12:13]
	s_mov_b64 exec, s[12:13]
	s_cbranch_execz .Lxb_done_12
	v_mov_b32_e32 v0, 0x21020
	ds_read2_b32 v[2:3], v0 offset1:1
	s_lshl_b32 s16, s84, 8
	s_add_u32 s16, s76, s16
	s_addc_u32 s17, s77, 0
	v_mov_b32_e32 v1, 0x1000
	v_mov_b32_e32 v4, 1
	global_atomic_add v5, v1, v4, s[16:17] offset:1024 sc0
	s_add_u32 s21, s99, 1
	s_waitcnt vmcnt(0) lgkmcnt(0)
	v_readfirstlane_b32 s18, v5
	v_readfirstlane_b32 s19, v2
	v_readfirstlane_b32 s20, v3
	v_mov_b32_e32 v1, 0x3000
	s_mul_i32 s22, s19, s21
	s_mul_i32 s23, s20, s21
	s_add_u32 s18, s18, 1
	s_cmp_lg_u32 s18, s22
	s_cbranch_scc1 .Lxb_spin_12
	buffer_wbl2 sc1
	s_waitcnt vmcnt(0)
	global_atomic_add v1, v4, s[76:77] offset:1024

.LBB0_1911:
	s_cmp_gt_i32 s79, 16
	s_cselect_b64 s[4:5], -1, 0
	s_and_b64 s[0:1], s[0:1], s[4:5]
	s_andn2_b64 vcc, exec, s[0:1]
	s_cbranch_vccnz .LBB0_1965
	s_waitcnt vmcnt(0) lgkmcnt(0)
	s_barrier
	v_readlane_b32 s12, v242, 1
	v_readlane_b32 s13, v242, 2
	s_mov_b64 s[14:15], exec
	s_and_b64 s[12:13], s[14:15], s[12:13]
	s_mov_b64 exec, s[12:13]
	s_cbranch_execz .Lxb_done_13
	v_mov_b32_e32 v0, 0x21020
	ds_read2_b32 v[2:3], v0 offset1:1
	s_lshl_b32 s16, s84, 8
	s_add_u32 s16, s76, s16
	s_addc_u32 s17, s77, 0
	v_mov_b32_e32 v1, 0x1000
	v_mov_b32_e32 v4, 1
	global_atomic_add v5, v1, v4, s[16:17] offset:1024 sc0
	s_add_u32 s21, s99, 1
	s_waitcnt vmcnt(0) lgkmcnt(0)
	v_readfirstlane_b32 s18, v5
	v_readfirstlane_b32 s19, v2
	v_readfirstlane_b32 s20, v3
	v_mov_b32_e32 v1, 0x3000
	s_mul_i32 s22, s19, s21
	s_mul_i32 s23, s20, s21
	s_add_u32 s18, s18, 1
	s_cmp_lg_u32 s18, s22
	s_cbranch_scc1 .Lxb_spin_13
	buffer_wbl2 sc1
	s_waitcnt vmcnt(0)
	global_atomic_add v1, v4, s[76:77] offset:1024

.LBB0_1982:
	s_cmp_gt_i32 s79, 17
	s_cselect_b64 s[4:5], -1, 0
	s_and_b64 s[0:1], s[0:1], s[4:5]
	s_andn2_b64 vcc, exec, s[0:1]
	s_cbranch_vccnz .LBB0_2036
	s_waitcnt vmcnt(0) lgkmcnt(0)
	s_barrier
	v_readlane_b32 s12, v242, 1
	v_readlane_b32 s13, v242, 2
	s_mov_b64 s[14:15], exec
	s_and_b64 s[12:13], s[14:15], s[12:13]
	s_mov_b64 exec, s[12:13]
	s_cbranch_execz .Lxb_done_14
	v_mov_b32_e32 v0, 0x21020
	ds_read2_b32 v[2:3], v0 offset1:1
	s_lshl_b32 s16, s84, 8
	s_add_u32 s16, s76, s16
	s_addc_u32 s17, s77, 0
	v_mov_b32_e32 v1, 0x1000
	v_mov_b32_e32 v4, 1
	global_atomic_add v5, v1, v4, s[16:17] offset:1024 sc0
	s_add_u32 s21, s99, 1
	s_waitcnt vmcnt(0) lgkmcnt(0)
	v_readfirstlane_b32 s18, v5
	v_readfirstlane_b32 s19, v2
	v_readfirstlane_b32 s20, v3
	v_mov_b32_e32 v1, 0x3000
	s_mul_i32 s22, s19, s21
	s_mul_i32 s23, s20, s21
	s_add_u32 s18, s18, 1
	s_cmp_lg_u32 s18, s22
	s_cbranch_scc1 .Lxb_spin_14
	buffer_wbl2 sc1
	s_waitcnt vmcnt(0)
	global_atomic_add v1, v4, s[76:77] offset:1024

	.amdhsa_kernel _Z10fwd_kernel4Args
		.amdhsa_group_segment_fixed_size 0
		.amdhsa_private_segment_fixed_size 0
		.amdhsa_kernarg_size 464
		.amdhsa_user_sgpr_count 2
		.amdhsa_user_sgpr_dispatch_ptr 0
		.amdhsa_user_sgpr_queue_ptr 0
		.amdhsa_user_sgpr_kernarg_segment_ptr 1
		.amdhsa_user_sgpr_dispatch_id 0
		.amdhsa_user_sgpr_kernarg_preload_length 0
		.amdhsa_user_sgpr_kernarg_preload_offset 0
		.amdhsa_user_sgpr_private_segment_size 0
		.amdhsa_uses_dynamic_stack 0
		.amdhsa_enable_private_segment 0
		.amdhsa_system_sgpr_workgroup_id_x 1
		.amdhsa_system_sgpr_workgroup_id_y 0
		.amdhsa_system_sgpr_workgroup_id_z 0
		.amdhsa_system_sgpr_workgroup_info 0
		.amdhsa_system_vgpr_workitem_id 2
		.amdhsa_next_free_vgpr 243
		.amdhsa_next_free_sgpr 102
		.amdhsa_accum_offset 244
		.amdhsa_reserve_vcc 1
		.amdhsa_float_round_mode_32 0
		.amdhsa_float_round_mode_16_64 0
		.amdhsa_float_denorm_mode_32 3
		.amdhsa_float_denorm_mode_16_64 3
		.amdhsa_dx10_clamp 1
		.amdhsa_ieee_mode 1
		.amdhsa_fp16_overflow 0
		.amdhsa_tg_split 0
		.amdhsa_exception_fp_ieee_invalid_op 0
		.amdhsa_exception_fp_denorm_src 0
		.amdhsa_exception_fp_ieee_div_zero 0
		.amdhsa_exception_fp_ieee_overflow 0
		.amdhsa_exception_fp_ieee_underflow 0
		.amdhsa_exception_fp_ieee_inexact 0
		.amdhsa_exception_int_div_zero 0
	.end_amdhsa_kernel

amdhsa.kernels:
  - .agpr_count:     0
    .args:
      - .offset:         0
        .size:           208
        .value_kind:     by_value
      - .offset:         208
        .size:           4
        .value_kind:     hidden_block_count_x
      - .offset:         212
        .size:           4
        .value_kind:     hidden_block_count_y
      - .offset:         216
        .size:           4
        .value_kind:     hidden_block_count_z
      - .offset:         220
        .size:           2
        .value_kind:     hidden_group_size_x
      - .offset:         222
        .size:           2
        .value_kind:     hidden_group_size_y
      - .offset:         224
        .size:           2
        .value_kind:     hidden_group_size_z
      - .offset:         226
        .size:           2
        .value_kind:     hidden_remainder_x
      - .offset:         228
        .size:           2
        .value_kind:     hidden_remainder_y
      - .offset:         230
        .size:           2
        .value_kind:     hidden_remainder_z
      - .offset:         248
        .size:           8
        .value_kind:     hidden_global_offset_x
      - .offset:         256
        .size:           8
        .value_kind:     hidden_global_offset_y
      - .offset:         264
        .size:           8
        .value_kind:     hidden_global_offset_z
      - .offset:         272
        .size:           2
        .value_kind:     hidden_grid_dims
      - .offset:         296
        .size:           8
        .value_kind:     hidden_multigrid_sync_arg
      - .offset:         328
        .size:           4
        .value_kind:     hidden_dynamic_lds_size
    .group_segment_fixed_size: 0
    .kernarg_segment_align: 8
    .kernarg_segment_size: 464
    .language:       OpenCL C
    .language_version:
      - 2
      - 0
    .max_flat_workgroup_size: 512
    .name:           _Z10fwd_kernel4Args
    .private_segment_fixed_size: 0
    .sgpr_count:     108
    .sgpr_spill_count: 64
    .symbol:         _Z10fwd_kernel4Args.kd
    .uniform_work_group_size: 1
    .uses_dynamic_stack: false
    .vgpr_count:     243
    .vgpr_spill_count: 0
    .wavefront_size: 64
